# resid gemm80 K-loop: LDS stage released mid-iteration, tile k+2 prefetched (two tiles in flight), counted vmcnt; J second round as single tiles; phase G gate loads issued before the K-loop
# speedup vs baseline: 1.0329x; 1.0109x over previous
.LdtJ_next:
	s_cmp_lg_u32 s22, 0x200
	s_cbranch_scc1 .LJd_generic
	s_cmp_gt_u32 s27, 0xff
	s_cbranch_scc1 .LJs_exit
	s_branch .LJs_outer
.LJd_generic:
	s_add_i32 s27, s27, s22
	s_cmp_gt_i32 s27, 639
	s_cbranch_scc0 .LBB0_21
	s_branch .LJs_exit
.LJs_outer:
	s_lshr_b32 s26, s27, 1
	s_addk_i32 s26, 0x200
	s_mul_hi_u32 s30, s26, 0xcccccccd
	s_lshr_b32 s30, s30, 4
	s_mul_i32 s28, s30, 20
	s_sub_i32 s36, s26, s28
	s_lshl_b32 s36, s36, 1
	s_and_b32 s28, s27, 1
	s_add_i32 s36, s36, s28
	v_mov_b32_e32 v2, v208
	s_ashr_i32 s37, s36, 31
	v_ashrrev_i32_e32 v3, 6, v2
	v_lshrrev_b32_e32 v0, 3, v2
	v_bfe_u32 v1, v2, 3, 3
	v_lshlrev_b32_e32 v5, 5, v3
	s_lshl_b64 s[40:41], s[36:37], 18
	v_readlane_b32 s44, v251, 27
	v_bitop3_b32 v4, v0, v2, 7 bitop3:0x28
	v_or_b32_e32 v0, v5, v1
	v_readlane_b32 s45, v251, 28
	s_add_u32 s40, s44, s40
	v_ashrrev_i32_e32 v1, 31, v0
	s_addc_u32 s41, s45, s41
	v_lshlrev_b64 v[0:1], 11, v[0:1]
	v_lshl_add_u64 v[0:1], s[40:41], 0, v[0:1]
	v_lshlrev_b32_e32 v128, 4, v4
	v_lshl_add_u64 v[64:65], v[0:1], 0, v[128:129]
	v_lshrrev_b32_e32 v0, 2, v2
	s_ashr_i32 s31, s30, 31
	v_and_b32_e32 v0, 8, v0
	v_bfe_u32 v1, v2, 3, 2
	s_lshl_b64 s[44:45], s[30:31], 18
	v_or3_b32 v0, v0, v1, v5
	s_add_u32 s44, s24, s44
	v_ashrrev_i32_e32 v1, 31, v0
	s_addc_u32 s45, s25, s45
	v_lshlrev_b64 v[0:1], 11, v[0:1]
	v_lshl_add_u64 v[0:1], s[44:45], 0, v[0:1]
	v_lshlrev_b32_e32 v80, 12, v3
	v_lshl_add_u64 v[66:67], v[0:1], 0, v[128:129]
	v_readfirstlane_b32 s26, v80
	v_or_b32_e32 v0, 0x400, v80
	s_waitcnt lgkmcnt(0)
	s_barrier
	s_mov_b32 m0, s26
	s_mov_b64 s[40:41], 0x4000
	v_readfirstlane_b32 s26, v0
	v_or_b32_e32 v0, 0x800, v80
	global_load_lds_dwordx4 v[64:65], off
	v_lshl_add_u64 v[68:69], v[64:65], 0, s[40:41]
	s_mov_b32 m0, s26
	s_mov_b64 s[40:41], 0x8000
	v_readfirstlane_b32 s26, v0
	v_or_b32_e32 v0, 0xc00, v80
	global_load_lds_dwordx4 v[68:69], off
	v_lshl_add_u64 v[70:71], v[64:65], 0, s[40:41]
	s_mov_b32 m0, s26
	s_mov_b64 s[44:45], 0xc000
	v_readfirstlane_b32 s26, v0
	v_add_u32_e32 v0, 0x4000, v80
	global_load_lds_dwordx4 v[70:71], off
	v_lshl_add_u64 v[72:73], v[64:65], 0, s[44:45]
	s_mov_b32 m0, s26
	v_readfirstlane_b32 s26, v0
	v_add_u32_e32 v0, 0x4400, v80
	global_load_lds_dwordx4 v[72:73], off
	s_mov_b32 m0, s26
	v_readfirstlane_b32 s26, v0
	v_add_u32_e32 v0, 0x4800, v80
	global_load_lds_dwordx4 v[66:67], off
	v_lshl_add_u64 v[74:75], v[66:67], 0, s[40:41]
	s_mov_b32 m0, s26
	s_mov_b64 s[40:41], 0x2000
	v_readfirstlane_b32 s26, v0
	v_add_u32_e32 v0, 0x4c00, v80
	global_load_lds_dwordx4 v[74:75], off
	v_lshl_add_u64 v[76:77], v[66:67], 0, s[40:41]
	s_mov_b32 m0, s26
	s_mov_b64 s[40:41], 0xa000
	v_readfirstlane_b32 s26, v0
	global_load_lds_dwordx4 v[76:77], off
	v_lshl_add_u64 v[78:79], v[66:67], 0, s[40:41]
	s_mov_b32 m0, s26
	v_and_b32_e32 v0, 7, v2
	global_load_lds_dwordx4 v[78:79], off
	v_lshlrev_b32_e32 v1, 7, v2
	v_lshlrev_b32_e32 v0, 4, v0
	v_and_b32_e32 v1, 0x780, v1
	v_bitop3_b32 v0, v0, v2, 48 bitop3:0x78
	v_or_b32_e32 v81, v0, v1
	v_bitop3_b32 v82, v0, 64, v1 bitop3:0x36
	v_lshlrev_b32_e32 v0, 6, v2
	v_and_b32_e32 v83, 0xffffe000, v0
	v_lshlrev_b32_e32 v0, 13, v3
	v_and_b32_e32 v0, 0x2000, v0
	v_or_b32_e32 v84, 0x4000, v0
	v_mov_b32_e32 v0, 0
	s_mov_b32 s26, 64
	s_mov_b32 s31, 0
	v_mov_b32_e32 v1, v0
	v_mov_b32_e32 v2, v0
	v_mov_b32_e32 v3, v0
	v_mov_b32_e32 v4, v0
	v_mov_b32_e32 v5, v0
	v_mov_b32_e32 v6, v0
	v_mov_b32_e32 v7, v0
	v_mov_b32_e32 v8, v0
	v_mov_b32_e32 v9, v0
	v_mov_b32_e32 v10, v0
	v_mov_b32_e32 v11, v0
	v_mov_b32_e32 v12, v0
	v_mov_b32_e32 v13, v0
	v_mov_b32_e32 v14, v0
	v_mov_b32_e32 v15, v0
	v_mov_b32_e32 v16, v0
	v_mov_b32_e32 v17, v0
	v_mov_b32_e32 v18, v0
	v_mov_b32_e32 v19, v0
	v_mov_b32_e32 v20, v0
	v_mov_b32_e32 v21, v0
	v_mov_b32_e32 v22, v0
	v_mov_b32_e32 v23, v0
	v_mov_b32_e32 v24, v0
	v_mov_b32_e32 v25, v0
	v_mov_b32_e32 v26, v0
	v_mov_b32_e32 v27, v0
	v_mov_b32_e32 v28, v0
	v_mov_b32_e32 v29, v0
	v_mov_b32_e32 v30, v0
	v_mov_b32_e32 v31, v0
	v_mov_b32_e32 v32, v0
	v_mov_b32_e32 v33, v0
	v_mov_b32_e32 v34, v0
	v_mov_b32_e32 v35, v0
	v_mov_b32_e32 v36, v0
	v_mov_b32_e32 v37, v0
	v_mov_b32_e32 v38, v0
	v_mov_b32_e32 v39, v0
	v_mov_b32_e32 v40, v0
	v_mov_b32_e32 v41, v0
	v_mov_b32_e32 v42, v0
	v_mov_b32_e32 v43, v0
	v_mov_b32_e32 v44, v0
	v_mov_b32_e32 v45, v0
	v_mov_b32_e32 v46, v0
	v_mov_b32_e32 v47, v0
	v_mov_b32_e32 v48, v0
	v_mov_b32_e32 v49, v0
	v_mov_b32_e32 v50, v0
	v_mov_b32_e32 v51, v0
	v_mov_b32_e32 v52, v0
	v_mov_b32_e32 v53, v0
	v_mov_b32_e32 v54, v0
	v_mov_b32_e32 v55, v0
	v_mov_b32_e32 v56, v0
	v_mov_b32_e32 v57, v0
	v_mov_b32_e32 v58, v0
	v_mov_b32_e32 v59, v0
	v_mov_b32_e32 v60, v0
	v_mov_b32_e32 v61, v0
	v_mov_b32_e32 v62, v0
	v_mov_b32_e32 v63, v0
.LJs_inner:
	s_add_i32 s28, s31, 0x8000
	s_and_b32 s37, s28, 0x8000
	s_min_i32 s40, s26, 0x3c0
	v_add_u32_e32 v85, s37, v80
	s_ashr_i32 s41, s40, 31
	s_waitcnt vmcnt(0)
	s_lshl_b64 s[40:41], s[40:41], 1
	v_readfirstlane_b32 s37, v85
	v_add_u32_e32 v88, 0x400, v85
	s_waitcnt lgkmcnt(0)
	s_barrier
	v_lshl_add_u64 v[86:87], v[64:65], 0, s[40:41]
	s_mov_b32 m0, s37
	v_readfirstlane_b32 s37, v88
	v_add_u32_e32 v88, 0x800, v85
	global_load_lds_dwordx4 v[86:87], off
	v_lshl_add_u64 v[86:87], v[68:69], 0, s[40:41]
	s_mov_b32 m0, s37
	v_readfirstlane_b32 s37, v88
	v_add_u32_e32 v88, 0xc00, v85
	global_load_lds_dwordx4 v[86:87], off
	v_lshl_add_u64 v[86:87], v[70:71], 0, s[40:41]
	s_mov_b32 m0, s37
	v_readfirstlane_b32 s37, v88
	v_add_u32_e32 v88, 0x4000, v85
	global_load_lds_dwordx4 v[86:87], off
	v_lshl_add_u64 v[86:87], v[72:73], 0, s[40:41]
	s_mov_b32 m0, s37
	v_readfirstlane_b32 s37, v88
	v_add_u32_e32 v88, 0x4400, v85
	global_load_lds_dwordx4 v[86:87], off
	v_lshl_add_u64 v[86:87], v[66:67], 0, s[40:41]
	s_mov_b32 m0, s37
	v_readfirstlane_b32 s37, v88
	v_add_u32_e32 v88, 0x4800, v85
	global_load_lds_dwordx4 v[86:87], off
	v_lshl_add_u64 v[86:87], v[74:75], 0, s[40:41]
	s_mov_b32 m0, s37
	v_readfirstlane_b32 s37, v88
	v_add_u32_e32 v85, 0x4c00, v85
	global_load_lds_dwordx4 v[86:87], off
	v_lshl_add_u64 v[86:87], v[76:77], 0, s[40:41]
	s_mov_b32 m0, s37
	v_readfirstlane_b32 s37, v85
	global_load_lds_dwordx4 v[86:87], off
	v_lshl_add_u64 v[86:87], v[78:79], 0, s[40:41]
	s_mov_b32 m0, s37
	s_and_b32 s31, s31, 0x8000
	global_load_lds_dwordx4 v[86:87], off
	v_add_u32_e32 v85, s31, v83
	v_or_b32_e32 v86, s31, v84
	v_add_u32_e32 v126, v85, v81
	v_add_u32_e32 v85, v85, v82
	v_add_u32_e32 v127, v86, v81
	v_add_u32_e32 v128, v86, v82
	ds_read_b128 v[86:89], v126
	ds_read_b128 v[90:93], v126 offset:2048
	ds_read_b128 v[94:97], v126 offset:4096
	ds_read_b128 v[98:101], v126 offset:6144
	ds_read_b128 v[102:105], v127
	ds_read_b128 v[106:109], v127 offset:2048
	ds_read_b128 v[110:113], v127 offset:4096
	ds_read_b128 v[114:117], v127 offset:6144
	ds_read_b128 v[118:121], v85
	ds_read_b128 v[122:125], v85 offset:2048
	ds_read_b128 v[134:137], v85 offset:4096
	ds_read_b128 v[138:141], v85 offset:6144
	ds_read_b128 v[142:145], v128
	ds_read_b128 v[146:149], v128 offset:2048
	ds_read_b128 v[150:153], v128 offset:4096
	ds_read_b128 v[154:157], v128 offset:6144
	s_waitcnt lgkmcnt(8)
	s_add_i32 s26, s26, 64
	v_mfma_f32_16x16x32_bf16 v[60:63], v[102:105], v[86:89], v[60:63]
	s_cmp_lg_u32 s28, 0x80000
	s_mov_b32 s31, s28
	v_mfma_f32_16x16x32_bf16 v[56:59], v[106:109], v[86:89], v[56:59]
	v_mfma_f32_16x16x32_bf16 v[52:55], v[110:113], v[86:89], v[52:55]
	v_mfma_f32_16x16x32_bf16 v[48:51], v[114:117], v[86:89], v[48:51]
	v_mfma_f32_16x16x32_bf16 v[44:47], v[102:105], v[90:93], v[44:47]
	v_mfma_f32_16x16x32_bf16 v[40:43], v[106:109], v[90:93], v[40:43]
	v_mfma_f32_16x16x32_bf16 v[36:39], v[110:113], v[90:93], v[36:39]
	v_mfma_f32_16x16x32_bf16 v[32:35], v[114:117], v[90:93], v[32:35]
	v_mfma_f32_16x16x32_bf16 v[28:31], v[102:105], v[94:97], v[28:31]
	v_mfma_f32_16x16x32_bf16 v[24:27], v[106:109], v[94:97], v[24:27]
	v_mfma_f32_16x16x32_bf16 v[20:23], v[110:113], v[94:97], v[20:23]
	v_mfma_f32_16x16x32_bf16 v[12:15], v[102:105], v[98:101], v[12:15]
	v_mfma_f32_16x16x32_bf16 v[8:11], v[106:109], v[98:101], v[8:11]
	v_mfma_f32_16x16x32_bf16 v[4:7], v[110:113], v[98:101], v[4:7]
	v_mfma_f32_16x16x32_bf16 v[0:3], v[114:117], v[98:101], v[0:3]
	v_mfma_f32_16x16x32_bf16 v[16:19], v[114:117], v[94:97], v[16:19]
	s_waitcnt lgkmcnt(0)
	s_nop 0
	v_mfma_f32_16x16x32_bf16 v[60:63], v[142:145], v[118:121], v[60:63]
	v_mfma_f32_16x16x32_bf16 v[56:59], v[146:149], v[118:121], v[56:59]
	v_mfma_f32_16x16x32_bf16 v[52:55], v[150:153], v[118:121], v[52:55]
	v_mfma_f32_16x16x32_bf16 v[48:51], v[154:157], v[118:121], v[48:51]
	v_mfma_f32_16x16x32_bf16 v[44:47], v[142:145], v[122:125], v[44:47]
	v_mfma_f32_16x16x32_bf16 v[40:43], v[146:149], v[122:125], v[40:43]
	v_mfma_f32_16x16x32_bf16 v[36:39], v[150:153], v[122:125], v[36:39]
	v_mfma_f32_16x16x32_bf16 v[32:35], v[154:157], v[122:125], v[32:35]
	v_mfma_f32_16x16x32_bf16 v[28:31], v[142:145], v[134:137], v[28:31]
	v_mfma_f32_16x16x32_bf16 v[24:27], v[146:149], v[134:137], v[24:27]
	v_mfma_f32_16x16x32_bf16 v[20:23], v[150:153], v[134:137], v[20:23]
	v_mfma_f32_16x16x32_bf16 v[16:19], v[154:157], v[134:137], v[16:19]
	v_mfma_f32_16x16x32_bf16 v[12:15], v[142:145], v[138:141], v[12:15]
	v_mfma_f32_16x16x32_bf16 v[8:11], v[146:149], v[138:141], v[8:11]
	v_mfma_f32_16x16x32_bf16 v[4:7], v[150:153], v[138:141], v[4:7]
	v_mfma_f32_16x16x32_bf16 v[0:3], v[154:157], v[138:141], v[0:3]
	s_cbranch_scc1 .LJs_inner
	s_waitcnt vmcnt(0)
	v_mov_b32_e32 v64, v208
	s_waitcnt lgkmcnt(0)
	s_barrier
	v_mov_b32_e32 v65, v208
	v_and_b32_e32 v67, 15, v64
	v_lshrrev_b32_e32 v64, 1, v64
	v_and_b32_e32 v64, 24, v64
	v_max_f32_e32 v60, v60, v60
	v_max_f32_e32 v61, v61, v61
	v_max_f32_e32 v62, v62, v62
	v_max_f32_e32 v63, v63, v63
	v_max_f32_e32 v56, v56, v56
	v_max_f32_e32 v57, v57, v57
	v_max_f32_e32 v58, v58, v58
	v_max_f32_e32 v60, 0, v60
	v_and_or_b32 v68, v65, 64, v64
	v_max_f32_e32 v61, 0, v61
	v_max_f32_e32 v62, 0, v62
	v_max_f32_e32 v63, 0, v63
	v_max_f32_e32 v56, 0, v56
	v_max_f32_e32 v57, 0, v57
	v_max_f32_e32 v64, 0, v58
	v_max_f32_e32 v58, v59, v59
	v_ashrrev_i32_e32 v66, 1, v65
	s_movk_i32 s26, 0xffc0
	v_max_f32_e32 v65, 0, v58
	v_pk_mul_f32 v[58:59], v[60:61], v[60:61]
	v_pk_mul_f32 v[60:61], v[62:63], v[62:63]
	v_pk_mul_f32 v[56:57], v[56:57], v[56:57]
	v_and_or_b32 v66, v66, s26, v67
	v_cvt_pk_bf16_f32 v58, v58, v59
	v_cvt_pk_bf16_f32 v59, v60, v61
	v_cvt_pk_bf16_f32 v60, v56, v57
	v_pk_mul_f32 v[56:57], v[64:65], v[64:65]
	s_lshl_b32 s30, s30, 7
	v_cvt_pk_bf16_f32 v61, v56, v57
	v_lshl_add_u32 v56, s36, 7, v66
	v_ashrrev_i32_e32 v57, 31, v56
	v_lshlrev_b64 v[62:63], 13, v[56:57]
	s_ashr_i32 s31, s30, 31
	v_lshl_add_u64 v[62:63], s[70:71], 0, v[62:63]
	s_lshl_b64 s[30:31], s[30:31], 1
	v_lshl_add_u64 v[62:63], v[62:63], 0, s[30:31]
	v_lshlrev_b32_e32 v128, 1, v68
	v_lshl_add_u64 v[62:63], v[62:63], 0, v[128:129]
	v_max_f32_e32 v48, v48, v48
	global_store_dwordx4 v[62:63], v[58:61], off
	v_max_f32_e32 v52, v52, v52
	v_max_f32_e32 v53, v53, v53
	v_max_f32_e32 v58, 0, v48
	v_max_f32_e32 v48, v49, v49
	v_max_f32_e32 v54, v54, v54
	v_max_f32_e32 v55, v55, v55
	v_max_f32_e32 v59, 0, v48
	v_max_f32_e32 v48, v50, v50
	v_max_f32_e32 v52, 0, v52
	v_max_f32_e32 v53, 0, v53
	v_max_f32_e32 v54, 0, v54
	v_max_f32_e32 v55, 0, v55
	v_max_f32_e32 v60, 0, v48
	v_max_f32_e32 v48, v51, v51
	v_max_f32_e32 v61, 0, v48
	v_pk_mul_f32 v[48:49], v[52:53], v[52:53]
	v_pk_mul_f32 v[50:51], v[54:55], v[54:55]
	v_cvt_pk_bf16_f32 v48, v48, v49
	v_cvt_pk_bf16_f32 v49, v50, v51
	v_pk_mul_f32 v[50:51], v[58:59], v[58:59]
	v_pk_mul_f32 v[52:53], v[60:61], v[60:61]
	v_cvt_pk_bf16_f32 v50, v50, v51
	v_cvt_pk_bf16_f32 v51, v52, v53
	v_max_f32_e32 v40, v40, v40
	global_store_dwordx4 v[62:63], v[48:51], off offset:64
	v_max_f32_e32 v44, v44, v44
	v_max_f32_e32 v45, v45, v45
	v_max_f32_e32 v48, 0, v40
	v_max_f32_e32 v40, v41, v41
	v_max_f32_e32 v46, v46, v46
	v_max_f32_e32 v47, v47, v47
	v_max_f32_e32 v49, 0, v40
	v_max_f32_e32 v40, v42, v42
	v_max_f32_e32 v44, 0, v44
	v_max_f32_e32 v45, 0, v45
	v_max_f32_e32 v46, 0, v46
	v_max_f32_e32 v47, 0, v47
	v_max_f32_e32 v50, 0, v40
	v_max_f32_e32 v40, v43, v43
	v_max_f32_e32 v51, 0, v40
	v_pk_mul_f32 v[40:41], v[44:45], v[44:45]
	v_pk_mul_f32 v[42:43], v[46:47], v[46:47]
	v_cvt_pk_bf16_f32 v40, v40, v41
	v_cvt_pk_bf16_f32 v41, v42, v43
	v_pk_mul_f32 v[42:43], v[48:49], v[48:49]
	v_pk_mul_f32 v[44:45], v[50:51], v[50:51]
	v_cvt_pk_bf16_f32 v42, v42, v43
	v_cvt_pk_bf16_f32 v43, v44, v45
	v_or_b32_e32 v44, 16, v56
	v_ashrrev_i32_e32 v45, 31, v44
	v_lshlrev_b64 v[44:45], 13, v[44:45]
	v_lshl_add_u64 v[44:45], s[70:71], 0, v[44:45]
	v_lshl_add_u64 v[44:45], v[44:45], 0, s[30:31]
	v_lshl_add_u64 v[44:45], v[44:45], 0, v[128:129]
	v_max_f32_e32 v32, v32, v32
	global_store_dwordx4 v[44:45], v[40:43], off
	v_max_f32_e32 v36, v36, v36
	v_max_f32_e32 v37, v37, v37
	v_max_f32_e32 v40, 0, v32
	v_max_f32_e32 v32, v33, v33
	v_max_f32_e32 v38, v38, v38
	v_max_f32_e32 v39, v39, v39
	v_max_f32_e32 v41, 0, v32
	v_max_f32_e32 v32, v34, v34
	v_max_f32_e32 v36, 0, v36
	v_max_f32_e32 v37, 0, v37
	v_max_f32_e32 v38, 0, v38
	v_max_f32_e32 v39, 0, v39
	v_max_f32_e32 v42, 0, v32
	v_max_f32_e32 v32, v35, v35
	v_max_f32_e32 v43, 0, v32
	v_pk_mul_f32 v[32:33], v[36:37], v[36:37]
	v_pk_mul_f32 v[34:35], v[38:39], v[38:39]
	v_cvt_pk_bf16_f32 v32, v32, v33
	v_cvt_pk_bf16_f32 v33, v34, v35
	v_pk_mul_f32 v[34:35], v[40:41], v[40:41]
	v_pk_mul_f32 v[36:37], v[42:43], v[42:43]
	v_cvt_pk_bf16_f32 v34, v34, v35
	v_cvt_pk_bf16_f32 v35, v36, v37
	v_max_f32_e32 v24, v24, v24
	global_store_dwordx4 v[44:45], v[32:35], off offset:64
	v_max_f32_e32 v28, v28, v28
	v_max_f32_e32 v29, v29, v29
	v_max_f32_e32 v32, 0, v24
	v_max_f32_e32 v24, v25, v25
	v_max_f32_e32 v30, v30, v30
	v_max_f32_e32 v31, v31, v31
	v_max_f32_e32 v33, 0, v24
	v_max_f32_e32 v24, v26, v26
	v_max_f32_e32 v28, 0, v28
	v_max_f32_e32 v29, 0, v29
	v_max_f32_e32 v30, 0, v30
	v_max_f32_e32 v31, 0, v31
	v_max_f32_e32 v34, 0, v24
	v_max_f32_e32 v24, v27, v27
	v_max_f32_e32 v35, 0, v24
	v_pk_mul_f32 v[24:25], v[28:29], v[28:29]
	v_pk_mul_f32 v[26:27], v[30:31], v[30:31]
	v_cvt_pk_bf16_f32 v24, v24, v25
	v_cvt_pk_bf16_f32 v25, v26, v27
	v_pk_mul_f32 v[26:27], v[32:33], v[32:33]
	v_pk_mul_f32 v[28:29], v[34:35], v[34:35]
	v_cvt_pk_bf16_f32 v26, v26, v27
	v_cvt_pk_bf16_f32 v27, v28, v29
	v_or_b32_e32 v28, 32, v56
	v_ashrrev_i32_e32 v29, 31, v28
	v_lshlrev_b64 v[28:29], 13, v[28:29]
	v_lshl_add_u64 v[28:29], s[70:71], 0, v[28:29]
	v_lshl_add_u64 v[28:29], v[28:29], 0, s[30:31]
	v_lshl_add_u64 v[28:29], v[28:29], 0, v[128:129]
	v_max_f32_e32 v16, v16, v16
	global_store_dwordx4 v[28:29], v[24:27], off
	v_max_f32_e32 v20, v20, v20
	v_max_f32_e32 v21, v21, v21
	v_max_f32_e32 v24, 0, v16
	v_max_f32_e32 v16, v17, v17
	v_max_f32_e32 v22, v22, v22
	v_max_f32_e32 v23, v23, v23
	v_max_f32_e32 v25, 0, v16
	v_max_f32_e32 v16, v18, v18
	v_max_f32_e32 v20, 0, v20
	v_max_f32_e32 v21, 0, v21
	v_max_f32_e32 v22, 0, v22
	v_max_f32_e32 v23, 0, v23
	v_max_f32_e32 v26, 0, v16
	v_max_f32_e32 v16, v19, v19
	v_max_f32_e32 v27, 0, v16
	v_pk_mul_f32 v[16:17], v[20:21], v[20:21]
	v_pk_mul_f32 v[18:19], v[22:23], v[22:23]
	v_cvt_pk_bf16_f32 v16, v16, v17
	v_cvt_pk_bf16_f32 v17, v18, v19
	v_pk_mul_f32 v[18:19], v[24:25], v[24:25]
	v_pk_mul_f32 v[20:21], v[26:27], v[26:27]
	v_cvt_pk_bf16_f32 v18, v18, v19
	v_cvt_pk_bf16_f32 v19, v20, v21
	v_max_f32_e32 v8, v8, v8
	global_store_dwordx4 v[28:29], v[16:19], off offset:64
	v_max_f32_e32 v12, v12, v12
	v_max_f32_e32 v13, v13, v13
	v_max_f32_e32 v16, 0, v8
	v_max_f32_e32 v8, v9, v9
	v_max_f32_e32 v14, v14, v14
	v_max_f32_e32 v15, v15, v15
	v_max_f32_e32 v17, 0, v8
	v_max_f32_e32 v8, v10, v10
	v_max_f32_e32 v12, 0, v12
	v_max_f32_e32 v13, 0, v13
	v_max_f32_e32 v14, 0, v14
	v_max_f32_e32 v15, 0, v15
	v_max_f32_e32 v18, 0, v8
	v_max_f32_e32 v8, v11, v11
	v_max_f32_e32 v19, 0, v8
	v_pk_mul_f32 v[8:9], v[12:13], v[12:13]
	v_pk_mul_f32 v[10:11], v[14:15], v[14:15]
	v_cvt_pk_bf16_f32 v8, v8, v9
	v_cvt_pk_bf16_f32 v9, v10, v11
	v_pk_mul_f32 v[10:11], v[16:17], v[16:17]
	v_pk_mul_f32 v[12:13], v[18:19], v[18:19]
	v_cvt_pk_bf16_f32 v10, v10, v11
	v_cvt_pk_bf16_f32 v11, v12, v13
	v_or_b32_e32 v12, 48, v56
	v_ashrrev_i32_e32 v13, 31, v12
	v_lshlrev_b64 v[12:13], 13, v[12:13]
	v_lshl_add_u64 v[12:13], s[70:71], 0, v[12:13]
	v_lshl_add_u64 v[12:13], v[12:13], 0, s[30:31]
	v_lshl_add_u64 v[12:13], v[12:13], 0, v[128:129]
	v_max_f32_e32 v0, v0, v0
	global_store_dwordx4 v[12:13], v[8:11], off
	v_max_f32_e32 v4, v4, v4
	v_max_f32_e32 v5, v5, v5
	v_max_f32_e32 v8, 0, v0
	v_max_f32_e32 v0, v1, v1
	v_max_f32_e32 v6, v6, v6
	v_max_f32_e32 v7, v7, v7
	v_max_f32_e32 v9, 0, v0
	v_max_f32_e32 v0, v2, v2
	v_max_f32_e32 v4, 0, v4
	v_max_f32_e32 v5, 0, v5
	v_max_f32_e32 v6, 0, v6
	v_max_f32_e32 v7, 0, v7
	v_max_f32_e32 v10, 0, v0
	v_max_f32_e32 v0, v3, v3
	v_max_f32_e32 v11, 0, v0
	v_pk_mul_f32 v[0:1], v[4:5], v[4:5]
	v_pk_mul_f32 v[2:3], v[6:7], v[6:7]
	v_cvt_pk_bf16_f32 v0, v0, v1
	v_cvt_pk_bf16_f32 v1, v2, v3
	v_pk_mul_f32 v[2:3], v[8:9], v[8:9]
	v_pk_mul_f32 v[4:5], v[10:11], v[10:11]
	v_cvt_pk_bf16_f32 v2, v2, v3
	v_cvt_pk_bf16_f32 v3, v4, v5
	global_store_dwordx4 v[12:13], v[0:3], off offset:64
.LJs_exit:
.LBB0_24:
	v_readlane_b32 s24, v255, 43
	s_add_i32 s24, s24, 41
	s_cmpk_lt_u32 s24, 0x57
	v_readlane_b32 s26, v251, 5
	s_cselect_b64 s[24:25], -1, 0
	v_readlane_b32 s27, v251, 6
	s_and_b64 s[24:25], s[26:27], s[24:25]
	s_and_b64 vcc, exec, s[24:25]
	s_cbranch_vccz .LBB0_71
	s_mul_i32 s26, s56, 0x46e
	s_min_i32 s24, s26, 0xd4a
	v_readlane_b32 s25, v251, 31
	s_addk_i32 s24, 0x46e
	s_add_i32 s25, s25, s26
	s_cmp_lt_i32 s25, s24
	v_readlane_b32 s36, v251, 29
	s_cselect_b64 s[30:31], -1, 0
	v_readlane_b32 s37, v251, 30
	s_and_b64 s[30:31], s[36:37], s[30:31]
	s_andn2_b64 vcc, exec, s[30:31]
	s_cbranch_vccnz .LBB0_71
	v_readlane_b32 s27, v254, 55
	s_add_i32 s26, s27, s26
	s_mov_b32 s42, s92
	s_branch .LBB0_30

.LBB0_83:
	s_lshl_b32 s28, s51, 11
	s_waitcnt lgkmcnt(0)
	s_barrier
	v_lshl_add_u64 v[94:95], v[54:55], 0, s[28:29]
	v_mov_b32_e32 v94, v168
	v_mov_b32_e32 v95, v169
	v_mov_b32_e32 v96, v170
	v_mov_b32_e32 v97, v171
	s_add_i32 s51, s51, 1
	s_add_u32 s30, s30, 0x400
	s_addc_u32 s31, s31, 0
	s_add_u32 s40, s40, 0x100000
	s_addc_u32 s41, s41, 0
	s_cmp_eq_u32 s51, 3
	s_waitcnt vmcnt(0)
	v_lshlrev_b32_e32 v45, 16, v94
	v_lshlrev_b32_e32 v99, 16, v95
	v_and_b32_e32 v100, 0xffff0000, v95
	v_lshlrev_b32_e32 v95, 16, v96
	v_mul_f32_e32 v45, 0xbfb8aa3b, v45
	v_and_b32_e32 v98, 0xffff0000, v94
	v_exp_f32_e32 v94, v45
	v_mul_f32_e32 v45, 0xbfb8aa3b, v95
	v_and_b32_e32 v101, 0xffff0000, v96
	v_exp_f32_e32 v96, v45
	v_mul_f32_e32 v45, 0xbfb8aa3b, v98
	v_exp_f32_e32 v95, v45
	v_lshlrev_b32_e32 v102, 16, v97
	v_and_b32_e32 v103, 0xffff0000, v97
	v_pk_add_f32 v[94:95], v[94:95], 1.0 op_sel_hi:[1,0]
	s_nop 0
	v_div_scale_f32 v45, s[24:25], v95, v95, 1.0
	v_rcp_f32_e32 v97, v45
	s_nop 0
	v_fma_f32 v98, -v45, v97, 1.0
	v_fmac_f32_e32 v97, v98, v97
	v_div_scale_f32 v98, vcc, 1.0, v95, 1.0
	v_mul_f32_e32 v104, v98, v97
	v_fma_f32 v105, -v45, v104, v98
	v_fmac_f32_e32 v104, v105, v97
	v_fma_f32 v45, -v45, v104, v98
	v_div_fmas_f32 v45, v45, v97, v104
	v_div_fixup_f32 v95, v45, v95, 1.0
	v_div_scale_f32 v45, s[24:25], v94, v94, 1.0
	v_rcp_f32_e32 v97, v45
	s_nop 0
	v_fma_f32 v98, -v45, v97, 1.0
	v_fmac_f32_e32 v97, v98, v97
	v_div_scale_f32 v98, vcc, 1.0, v94, 1.0
	v_mul_f32_e32 v104, v98, v97
	v_fma_f32 v105, -v45, v104, v98
	v_fmac_f32_e32 v104, v105, v97
	v_fma_f32 v45, -v45, v104, v98
	v_div_fmas_f32 v45, v45, v97, v104
	v_div_fixup_f32 v94, v45, v94, 1.0
	v_pk_fma_f32 v[90:91], v[36:37], v[94:95], v[90:91]
	v_mul_f32_e32 v36, 0xbfb8aa3b, v101
	v_exp_f32_e32 v97, v36
	s_nop 0
	v_pk_add_f32 v[36:37], v[96:97], 1.0 op_sel_hi:[1,0]
	s_nop 0
	v_div_scale_f32 v45, s[24:25], v37, v37, 1.0
	v_rcp_f32_e32 v94, v45
	s_nop 0
	v_fma_f32 v95, -v45, v94, 1.0
	v_fmac_f32_e32 v94, v95, v94
	v_div_scale_f32 v95, vcc, 1.0, v37, 1.0
	v_mul_f32_e32 v96, v95, v94
	v_fma_f32 v97, -v45, v96, v95
	v_fmac_f32_e32 v96, v97, v94
	v_fma_f32 v45, -v45, v96, v95
	v_div_fmas_f32 v45, v45, v94, v96
	v_div_fixup_f32 v37, v45, v37, 1.0
	v_div_scale_f32 v45, s[24:25], v36, v36, 1.0
	v_rcp_f32_e32 v94, v45
	s_nop 0
	v_fma_f32 v95, -v45, v94, 1.0
	v_fmac_f32_e32 v94, v95, v94
	v_div_scale_f32 v95, vcc, 1.0, v36, 1.0
	v_mul_f32_e32 v96, v95, v94
	v_fma_f32 v97, -v45, v96, v95
	v_fmac_f32_e32 v96, v97, v94
	v_fma_f32 v45, -v45, v96, v95
	v_div_fmas_f32 v45, v45, v94, v96
	v_div_fixup_f32 v36, v45, v36, 1.0
	v_pk_fma_f32 v[86:87], v[32:33], v[36:37], v[86:87]
	v_mul_f32_e32 v33, 0xbfb8aa3b, v102
	v_mul_f32_e32 v32, 0xbfb8aa3b, v99
	v_exp_f32_e32 v36, v33
	v_mul_f32_e32 v33, 0xbfb8aa3b, v100
	v_exp_f32_e32 v32, v32
	v_exp_f32_e32 v33, v33
	s_nop 0
	v_pk_add_f32 v[32:33], v[32:33], 1.0 op_sel_hi:[1,0]
	s_nop 0
	v_div_scale_f32 v37, s[24:25], v33, v33, 1.0
	v_rcp_f32_e32 v45, v37
	s_nop 0
	v_fma_f32 v94, -v37, v45, 1.0
	v_fmac_f32_e32 v45, v94, v45
	v_div_scale_f32 v94, vcc, 1.0, v33, 1.0
	v_mul_f32_e32 v95, v94, v45
	v_fma_f32 v96, -v37, v95, v94
	v_fmac_f32_e32 v95, v96, v45
	v_fma_f32 v37, -v37, v95, v94
	v_div_fmas_f32 v37, v37, v45, v95
	v_div_fixup_f32 v33, v37, v33, 1.0
	v_div_scale_f32 v37, s[24:25], v32, v32, 1.0
	v_rcp_f32_e32 v45, v37
	s_nop 0
	v_fma_f32 v94, -v37, v45, 1.0
	v_fmac_f32_e32 v45, v94, v45
	v_div_scale_f32 v94, vcc, 1.0, v32, 1.0
	v_mul_f32_e32 v95, v94, v45
	v_fma_f32 v96, -v37, v95, v94
	v_fmac_f32_e32 v95, v96, v45
	v_fma_f32 v37, -v37, v95, v94
	v_div_fmas_f32 v37, v37, v45, v95
	v_div_fixup_f32 v32, v37, v32, 1.0
	v_pk_fma_f32 v[92:93], v[38:39], v[32:33], v[92:93]
	v_mul_f32_e32 v32, 0xbfb8aa3b, v103
	v_exp_f32_e32 v37, v32
	s_nop 0
	v_pk_add_f32 v[32:33], v[36:37], 1.0 op_sel_hi:[1,0]
	s_nop 0
	v_div_scale_f32 v36, s[24:25], v33, v33, 1.0
	v_rcp_f32_e32 v37, v36
	s_nop 0
	v_fma_f32 v38, -v36, v37, 1.0
	v_fmac_f32_e32 v37, v38, v37
	v_div_scale_f32 v38, vcc, 1.0, v33, 1.0
	v_mul_f32_e32 v39, v38, v37
	v_fma_f32 v45, -v36, v39, v38
	v_fmac_f32_e32 v39, v45, v37
	v_fma_f32 v36, -v36, v39, v38
	v_div_fmas_f32 v36, v36, v37, v39
	v_div_fixup_f32 v33, v36, v33, 1.0
	v_div_scale_f32 v36, s[24:25], v32, v32, 1.0
	v_rcp_f32_e32 v37, v36
	s_nop 0
	v_fma_f32 v38, -v36, v37, 1.0
	v_fmac_f32_e32 v37, v38, v37
	v_div_scale_f32 v38, vcc, 1.0, v32, 1.0
	v_mul_f32_e32 v39, v38, v37
	v_fma_f32 v45, -v36, v39, v38
	v_fmac_f32_e32 v39, v45, v37
	v_fma_f32 v36, -v36, v39, v38
	v_div_fmas_f32 v36, v36, v37, v39
	v_div_fixup_f32 v32, v36, v32, 1.0
	v_pk_fma_f32 v[88:89], v[34:35], v[32:33], v[88:89]
	v_lshl_add_u64 v[32:33], v[62:63], 0, s[28:29]
	v_mov_b32_e32 v32, v172
	v_mov_b32_e32 v33, v173
	v_mov_b32_e32 v34, v174
	v_mov_b32_e32 v35, v175
	s_waitcnt vmcnt(0)
	v_lshlrev_b32_e32 v38, 16, v33
	v_and_b32_e32 v39, 0xffff0000, v33
	v_lshlrev_b32_e32 v33, 16, v34
	v_lshlrev_b32_e32 v36, 16, v32
	v_and_b32_e32 v37, 0xffff0000, v32
	v_mul_f32_e32 v33, 0xbfb8aa3b, v33
	v_and_b32_e32 v45, 0xffff0000, v34
	v_mul_f32_e32 v32, 0xbfb8aa3b, v36
	v_exp_f32_e32 v34, v33
	v_mul_f32_e32 v33, 0xbfb8aa3b, v37
	v_exp_f32_e32 v32, v32
	v_exp_f32_e32 v33, v33
	v_lshlrev_b32_e32 v94, 16, v35
	v_and_b32_e32 v95, 0xffff0000, v35
	v_pk_add_f32 v[32:33], v[32:33], 1.0 op_sel_hi:[1,0]
	s_nop 0
	v_div_scale_f32 v35, s[24:25], v33, v33, 1.0
	v_rcp_f32_e32 v36, v35
	s_nop 0
	v_fma_f32 v37, -v35, v36, 1.0
	v_fmac_f32_e32 v36, v37, v36
	v_div_scale_f32 v37, vcc, 1.0, v33, 1.0
	v_mul_f32_e32 v96, v37, v36
	v_fma_f32 v97, -v35, v96, v37
	v_fmac_f32_e32 v96, v97, v36
	v_fma_f32 v35, -v35, v96, v37
	v_div_fmas_f32 v35, v35, v36, v96
	v_div_fixup_f32 v33, v35, v33, 1.0
	v_div_scale_f32 v35, s[24:25], v32, v32, 1.0
	v_rcp_f32_e32 v36, v35
	s_nop 0
	v_fma_f32 v37, -v35, v36, 1.0
	v_fmac_f32_e32 v36, v37, v36
	v_div_scale_f32 v37, vcc, 1.0, v32, 1.0
	v_mul_f32_e32 v96, v37, v36
	v_fma_f32 v97, -v35, v96, v37
	v_fmac_f32_e32 v96, v97, v36
	v_fma_f32 v35, -v35, v96, v37
	v_div_fmas_f32 v35, v35, v36, v96
	v_div_fixup_f32 v32, v35, v32, 1.0
	v_pk_fma_f32 v[82:83], v[28:29], v[32:33], v[82:83]
	v_mul_f32_e32 v28, 0xbfb8aa3b, v45
	v_exp_f32_e32 v35, v28
	s_nop 0
	v_pk_add_f32 v[28:29], v[34:35], 1.0 op_sel_hi:[1,0]
	s_nop 0
	v_div_scale_f32 v32, s[24:25], v29, v29, 1.0
	v_rcp_f32_e32 v33, v32
	s_nop 0
	v_fma_f32 v34, -v32, v33, 1.0
	v_fmac_f32_e32 v33, v34, v33
	v_div_scale_f32 v34, vcc, 1.0, v29, 1.0
	v_mul_f32_e32 v35, v34, v33
	v_fma_f32 v36, -v32, v35, v34
	v_fmac_f32_e32 v35, v36, v33
	v_fma_f32 v32, -v32, v35, v34
	v_div_fmas_f32 v32, v32, v33, v35
	v_div_fixup_f32 v29, v32, v29, 1.0
	v_div_scale_f32 v32, s[24:25], v28, v28, 1.0
	v_rcp_f32_e32 v33, v32
	s_nop 0
	v_fma_f32 v34, -v32, v33, 1.0
	v_fmac_f32_e32 v33, v34, v33
	v_div_scale_f32 v34, vcc, 1.0, v28, 1.0
	v_mul_f32_e32 v35, v34, v33
	v_fma_f32 v36, -v32, v35, v34
	v_fmac_f32_e32 v35, v36, v33
	v_fma_f32 v32, -v32, v35, v34
	v_div_fmas_f32 v32, v32, v33, v35
	v_div_fixup_f32 v28, v32, v28, 1.0
	v_pk_fma_f32 v[78:79], v[24:25], v[28:29], v[78:79]
	v_mul_f32_e32 v25, 0xbfb8aa3b, v94
	v_mul_f32_e32 v24, 0xbfb8aa3b, v38
	v_exp_f32_e32 v28, v25
	v_mul_f32_e32 v25, 0xbfb8aa3b, v39
	v_exp_f32_e32 v24, v24
	v_exp_f32_e32 v25, v25
	s_nop 0
	v_pk_add_f32 v[24:25], v[24:25], 1.0 op_sel_hi:[1,0]
	s_nop 0
	v_div_scale_f32 v29, s[24:25], v25, v25, 1.0
	v_rcp_f32_e32 v32, v29
	s_nop 0
	v_fma_f32 v33, -v29, v32, 1.0
	v_fmac_f32_e32 v32, v33, v32
	v_div_scale_f32 v33, vcc, 1.0, v25, 1.0
	v_mul_f32_e32 v34, v33, v32
	v_fma_f32 v35, -v29, v34, v33
	v_fmac_f32_e32 v34, v35, v32
	v_fma_f32 v29, -v29, v34, v33
	v_div_fmas_f32 v29, v29, v32, v34
	v_div_fixup_f32 v25, v29, v25, 1.0
	v_div_scale_f32 v29, s[24:25], v24, v24, 1.0
	v_rcp_f32_e32 v32, v29
	s_nop 0
	v_fma_f32 v33, -v29, v32, 1.0
	v_fmac_f32_e32 v32, v33, v32
	v_div_scale_f32 v33, vcc, 1.0, v24, 1.0
	v_mul_f32_e32 v34, v33, v32
	v_fma_f32 v35, -v29, v34, v33
	v_fmac_f32_e32 v34, v35, v32
	v_fma_f32 v29, -v29, v34, v33
	v_div_fmas_f32 v29, v29, v32, v34
	v_div_fixup_f32 v24, v29, v24, 1.0
	v_pk_fma_f32 v[84:85], v[30:31], v[24:25], v[84:85]
	v_mul_f32_e32 v24, 0xbfb8aa3b, v95
	v_exp_f32_e32 v29, v24
	s_nop 0
	v_pk_add_f32 v[24:25], v[28:29], 1.0 op_sel_hi:[1,0]
	s_nop 0
	v_div_scale_f32 v28, s[24:25], v25, v25, 1.0
	v_rcp_f32_e32 v29, v28
	s_nop 0
	v_fma_f32 v30, -v28, v29, 1.0
	v_fmac_f32_e32 v29, v30, v29
	v_div_scale_f32 v30, vcc, 1.0, v25, 1.0
	v_mul_f32_e32 v31, v30, v29
	v_fma_f32 v32, -v28, v31, v30
	v_fmac_f32_e32 v31, v32, v29
	v_fma_f32 v28, -v28, v31, v30
	v_div_fmas_f32 v28, v28, v29, v31
	v_div_fixup_f32 v25, v28, v25, 1.0
	v_div_scale_f32 v28, s[24:25], v24, v24, 1.0
	v_rcp_f32_e32 v29, v28
	s_nop 0
	v_fma_f32 v30, -v28, v29, 1.0
	v_fmac_f32_e32 v29, v30, v29
	v_div_scale_f32 v30, vcc, 1.0, v24, 1.0
	v_mul_f32_e32 v31, v30, v29
	v_fma_f32 v32, -v28, v31, v30
	v_fmac_f32_e32 v31, v32, v29
	v_fma_f32 v28, -v28, v31, v30
	v_div_fmas_f32 v28, v28, v29, v31
	v_div_fixup_f32 v24, v28, v24, 1.0
	v_pk_fma_f32 v[80:81], v[26:27], v[24:25], v[80:81]
	v_lshl_add_u64 v[24:25], v[64:65], 0, s[28:29]
	v_mov_b32_e32 v24, v176
	v_mov_b32_e32 v25, v177
	v_mov_b32_e32 v26, v178
	v_mov_b32_e32 v27, v179
	s_waitcnt vmcnt(0)
	v_lshlrev_b32_e32 v30, 16, v25
	v_and_b32_e32 v31, 0xffff0000, v25
	v_lshlrev_b32_e32 v25, 16, v26
	v_lshlrev_b32_e32 v28, 16, v24
	v_and_b32_e32 v29, 0xffff0000, v24
	v_mul_f32_e32 v25, 0xbfb8aa3b, v25
	v_and_b32_e32 v32, 0xffff0000, v26
	v_mul_f32_e32 v24, 0xbfb8aa3b, v28
	v_exp_f32_e32 v26, v25
	v_mul_f32_e32 v25, 0xbfb8aa3b, v29
	v_exp_f32_e32 v24, v24
	v_exp_f32_e32 v25, v25
	v_lshlrev_b32_e32 v33, 16, v27
	v_and_b32_e32 v34, 0xffff0000, v27
	v_pk_add_f32 v[24:25], v[24:25], 1.0 op_sel_hi:[1,0]
	s_nop 0
	v_div_scale_f32 v27, s[24:25], v25, v25, 1.0
	v_rcp_f32_e32 v28, v27
	s_nop 0
	v_fma_f32 v29, -v27, v28, 1.0
	v_fmac_f32_e32 v28, v29, v28
	v_div_scale_f32 v29, vcc, 1.0, v25, 1.0
	v_mul_f32_e32 v35, v29, v28
	v_fma_f32 v36, -v27, v35, v29
	v_fmac_f32_e32 v35, v36, v28
	v_fma_f32 v27, -v27, v35, v29
	v_div_fmas_f32 v27, v27, v28, v35
	v_div_fixup_f32 v25, v27, v25, 1.0
	v_div_scale_f32 v27, s[24:25], v24, v24, 1.0
	v_rcp_f32_e32 v28, v27
	s_nop 0
	v_fma_f32 v29, -v27, v28, 1.0
	v_fmac_f32_e32 v28, v29, v28
	v_div_scale_f32 v29, vcc, 1.0, v24, 1.0
	v_mul_f32_e32 v35, v29, v28
	v_fma_f32 v36, -v27, v35, v29
	v_fmac_f32_e32 v35, v36, v28
	v_fma_f32 v27, -v27, v35, v29
	v_div_fmas_f32 v27, v27, v28, v35
	v_div_fixup_f32 v24, v27, v24, 1.0
	v_pk_fma_f32 v[74:75], v[20:21], v[24:25], v[74:75]
	v_mul_f32_e32 v20, 0xbfb8aa3b, v32
	v_exp_f32_e32 v27, v20
	s_nop 0
	v_pk_add_f32 v[20:21], v[26:27], 1.0 op_sel_hi:[1,0]
	s_nop 0
	v_div_scale_f32 v24, s[24:25], v21, v21, 1.0
	v_rcp_f32_e32 v25, v24
	s_nop 0
	v_fma_f32 v26, -v24, v25, 1.0
	v_fmac_f32_e32 v25, v26, v25
	v_div_scale_f32 v26, vcc, 1.0, v21, 1.0
	v_mul_f32_e32 v27, v26, v25
	v_fma_f32 v28, -v24, v27, v26
	v_fmac_f32_e32 v27, v28, v25
	v_fma_f32 v24, -v24, v27, v26
	v_div_fmas_f32 v24, v24, v25, v27
	v_div_fixup_f32 v21, v24, v21, 1.0
	v_div_scale_f32 v24, s[24:25], v20, v20, 1.0
	v_rcp_f32_e32 v25, v24
	s_nop 0
	v_fma_f32 v26, -v24, v25, 1.0
	v_fmac_f32_e32 v25, v26, v25
	v_div_scale_f32 v26, vcc, 1.0, v20, 1.0
	v_mul_f32_e32 v27, v26, v25
	v_fma_f32 v28, -v24, v27, v26
	v_fmac_f32_e32 v27, v28, v25
	v_fma_f32 v24, -v24, v27, v26
	v_div_fmas_f32 v24, v24, v25, v27
	v_div_fixup_f32 v20, v24, v20, 1.0
	v_pk_fma_f32 v[68:69], v[16:17], v[20:21], v[68:69]
	v_mul_f32_e32 v17, 0xbfb8aa3b, v33
	v_mul_f32_e32 v16, 0xbfb8aa3b, v30
	v_exp_f32_e32 v20, v17
	v_mul_f32_e32 v17, 0xbfb8aa3b, v31
	v_exp_f32_e32 v16, v16
	v_exp_f32_e32 v17, v17
	s_nop 0
	v_pk_add_f32 v[16:17], v[16:17], 1.0 op_sel_hi:[1,0]
	s_nop 0
	v_div_scale_f32 v21, s[24:25], v17, v17, 1.0
	v_rcp_f32_e32 v24, v21
	s_nop 0
	v_fma_f32 v25, -v21, v24, 1.0
	v_fmac_f32_e32 v24, v25, v24
	v_div_scale_f32 v25, vcc, 1.0, v17, 1.0
	v_mul_f32_e32 v26, v25, v24
	v_fma_f32 v27, -v21, v26, v25
	v_fmac_f32_e32 v26, v27, v24
	v_fma_f32 v21, -v21, v26, v25
	v_div_fmas_f32 v21, v21, v24, v26
	v_div_fixup_f32 v17, v21, v17, 1.0
	v_div_scale_f32 v21, s[24:25], v16, v16, 1.0
	v_rcp_f32_e32 v24, v21
	s_nop 0
	v_fma_f32 v25, -v21, v24, 1.0
	v_fmac_f32_e32 v24, v25, v24
	v_div_scale_f32 v25, vcc, 1.0, v16, 1.0
	v_mul_f32_e32 v26, v25, v24
	v_fma_f32 v27, -v21, v26, v25
	v_fmac_f32_e32 v26, v27, v24
	v_fma_f32 v21, -v21, v26, v25
	v_div_fmas_f32 v21, v21, v24, v26
	v_div_fixup_f32 v16, v21, v16, 1.0
	v_pk_fma_f32 v[76:77], v[22:23], v[16:17], v[76:77]
	v_mul_f32_e32 v16, 0xbfb8aa3b, v34
	v_exp_f32_e32 v21, v16
	s_nop 0
	v_pk_add_f32 v[16:17], v[20:21], 1.0 op_sel_hi:[1,0]
	s_nop 0
	v_div_scale_f32 v20, s[24:25], v17, v17, 1.0
	v_rcp_f32_e32 v21, v20
	s_nop 0
	v_fma_f32 v22, -v20, v21, 1.0
	v_fmac_f32_e32 v21, v22, v21
	v_div_scale_f32 v22, vcc, 1.0, v17, 1.0
	v_mul_f32_e32 v23, v22, v21
	v_fma_f32 v24, -v20, v23, v22
	v_fmac_f32_e32 v23, v24, v21
	v_fma_f32 v20, -v20, v23, v22
	v_div_fmas_f32 v20, v20, v21, v23
	v_div_fixup_f32 v17, v20, v17, 1.0
	v_div_scale_f32 v20, s[24:25], v16, v16, 1.0
	v_rcp_f32_e32 v21, v20
	s_nop 0
	v_fma_f32 v22, -v20, v21, 1.0
	v_fmac_f32_e32 v21, v22, v21
	v_div_scale_f32 v22, vcc, 1.0, v16, 1.0
	v_mul_f32_e32 v23, v22, v21
	v_fma_f32 v24, -v20, v23, v22
	v_fmac_f32_e32 v23, v24, v21
	v_fma_f32 v20, -v20, v23, v22
	v_div_fmas_f32 v20, v20, v21, v23
	v_div_fixup_f32 v16, v20, v16, 1.0
	v_pk_fma_f32 v[70:71], v[18:19], v[16:17], v[70:71]
	v_lshl_add_u64 v[16:17], v[66:67], 0, s[28:29]
	v_mov_b32_e32 v16, v180
	v_mov_b32_e32 v17, v181
	v_mov_b32_e32 v18, v182
	v_mov_b32_e32 v19, v183
	s_waitcnt vmcnt(0)
	v_lshlrev_b32_e32 v22, 16, v17
	v_and_b32_e32 v23, 0xffff0000, v17
	v_lshlrev_b32_e32 v17, 16, v18
	v_lshlrev_b32_e32 v20, 16, v16
	v_and_b32_e32 v21, 0xffff0000, v16
	v_mul_f32_e32 v17, 0xbfb8aa3b, v17
	v_and_b32_e32 v24, 0xffff0000, v18
	v_mul_f32_e32 v16, 0xbfb8aa3b, v20
	v_exp_f32_e32 v18, v17
	v_mul_f32_e32 v17, 0xbfb8aa3b, v21
	v_exp_f32_e32 v16, v16
	v_exp_f32_e32 v17, v17
	v_lshlrev_b32_e32 v25, 16, v19
	v_and_b32_e32 v26, 0xffff0000, v19
	v_pk_add_f32 v[16:17], v[16:17], 1.0 op_sel_hi:[1,0]
	s_nop 0
	v_div_scale_f32 v19, s[24:25], v17, v17, 1.0
	v_rcp_f32_e32 v20, v19
	s_nop 0
	v_fma_f32 v21, -v19, v20, 1.0
	v_fmac_f32_e32 v20, v21, v20
	v_div_scale_f32 v21, vcc, 1.0, v17, 1.0
	v_mul_f32_e32 v27, v21, v20
	v_fma_f32 v28, -v19, v27, v21
	v_fmac_f32_e32 v27, v28, v20
	v_fma_f32 v19, -v19, v27, v21
	v_div_fmas_f32 v19, v19, v20, v27
	v_div_fixup_f32 v17, v19, v17, 1.0
	v_div_scale_f32 v19, s[24:25], v16, v16, 1.0
	v_rcp_f32_e32 v20, v19
	s_nop 0
	v_fma_f32 v21, -v19, v20, 1.0
	v_fmac_f32_e32 v20, v21, v20
	v_div_scale_f32 v21, vcc, 1.0, v16, 1.0
	v_mul_f32_e32 v27, v21, v20
	v_fma_f32 v28, -v19, v27, v21
	v_fmac_f32_e32 v27, v28, v20
	v_fma_f32 v19, -v19, v27, v21
	v_div_fmas_f32 v19, v19, v20, v27
	v_div_fixup_f32 v16, v19, v16, 1.0
	v_pk_fma_f32 v[58:59], v[12:13], v[16:17], v[58:59]
	v_mul_f32_e32 v12, 0xbfb8aa3b, v24
	v_exp_f32_e32 v19, v12
	s_nop 0
	v_pk_add_f32 v[12:13], v[18:19], 1.0 op_sel_hi:[1,0]
	s_nop 0
	v_div_scale_f32 v16, s[24:25], v13, v13, 1.0
	v_rcp_f32_e32 v17, v16
	s_nop 0
	v_fma_f32 v18, -v16, v17, 1.0
	v_fmac_f32_e32 v17, v18, v17
	v_div_scale_f32 v18, vcc, 1.0, v13, 1.0
	v_mul_f32_e32 v19, v18, v17
	v_fma_f32 v20, -v16, v19, v18
	v_fmac_f32_e32 v19, v20, v17
	v_fma_f32 v16, -v16, v19, v18
	v_div_fmas_f32 v16, v16, v17, v19
	v_div_fixup_f32 v13, v16, v13, 1.0
	v_div_scale_f32 v16, s[24:25], v12, v12, 1.0
	v_rcp_f32_e32 v17, v16
	s_nop 0
	v_fma_f32 v18, -v16, v17, 1.0
	v_fmac_f32_e32 v17, v18, v17
	v_div_scale_f32 v18, vcc, 1.0, v12, 1.0
	v_mul_f32_e32 v19, v18, v17
	v_fma_f32 v20, -v16, v19, v18
	v_fmac_f32_e32 v19, v20, v17
	v_fma_f32 v16, -v16, v19, v18
	v_div_fmas_f32 v16, v16, v17, v19
	v_div_fixup_f32 v12, v16, v12, 1.0
	v_pk_fma_f32 v[52:53], v[8:9], v[12:13], v[52:53]
	v_mul_f32_e32 v9, 0xbfb8aa3b, v25
	v_mul_f32_e32 v8, 0xbfb8aa3b, v22
	v_exp_f32_e32 v12, v9
	v_mul_f32_e32 v9, 0xbfb8aa3b, v23
	v_exp_f32_e32 v8, v8
	v_exp_f32_e32 v9, v9
	s_nop 0
	v_pk_add_f32 v[8:9], v[8:9], 1.0 op_sel_hi:[1,0]
	s_nop 0
	v_div_scale_f32 v13, s[24:25], v9, v9, 1.0
	v_rcp_f32_e32 v16, v13
	s_nop 0
	v_fma_f32 v17, -v13, v16, 1.0
	v_fmac_f32_e32 v16, v17, v16
	v_div_scale_f32 v17, vcc, 1.0, v9, 1.0
	v_mul_f32_e32 v18, v17, v16
	v_fma_f32 v19, -v13, v18, v17
	v_fmac_f32_e32 v18, v19, v16
	v_fma_f32 v13, -v13, v18, v17
	v_div_fmas_f32 v13, v13, v16, v18
	v_div_fixup_f32 v9, v13, v9, 1.0
	v_div_scale_f32 v13, s[24:25], v8, v8, 1.0
	v_rcp_f32_e32 v16, v13
	s_nop 0
	v_fma_f32 v17, -v13, v16, 1.0
	v_fmac_f32_e32 v16, v17, v16
	v_div_scale_f32 v17, vcc, 1.0, v8, 1.0
	v_mul_f32_e32 v18, v17, v16
	v_fma_f32 v19, -v13, v18, v17
	v_fmac_f32_e32 v18, v19, v16
	v_fma_f32 v13, -v13, v18, v17
	v_div_fmas_f32 v13, v13, v16, v18
	v_div_fixup_f32 v8, v13, v8, 1.0
	v_pk_fma_f32 v[60:61], v[14:15], v[8:9], v[60:61]
	v_mul_f32_e32 v8, 0xbfb8aa3b, v26
	v_exp_f32_e32 v13, v8
	s_nop 0
	v_pk_add_f32 v[8:9], v[12:13], 1.0 op_sel_hi:[1,0]
	s_nop 0
	v_div_scale_f32 v12, s[24:25], v9, v9, 1.0
	v_rcp_f32_e32 v13, v12
	s_nop 0
	v_fma_f32 v14, -v12, v13, 1.0
	v_fmac_f32_e32 v13, v14, v13
	v_div_scale_f32 v14, vcc, 1.0, v9, 1.0
	v_mul_f32_e32 v15, v14, v13
	v_fma_f32 v16, -v12, v15, v14
	v_fmac_f32_e32 v15, v16, v13
	v_fma_f32 v12, -v12, v15, v14
	v_div_fmas_f32 v12, v12, v13, v15
	v_div_fixup_f32 v9, v12, v9, 1.0
	v_div_scale_f32 v12, s[24:25], v8, v8, 1.0
	v_rcp_f32_e32 v13, v12
	s_nop 0
	v_fma_f32 v14, -v12, v13, 1.0
	v_fmac_f32_e32 v13, v14, v13
	v_div_scale_f32 v14, vcc, 1.0, v8, 1.0
	v_mul_f32_e32 v15, v14, v13
	v_fma_f32 v16, -v12, v15, v14
	v_fmac_f32_e32 v15, v16, v13
	v_fma_f32 v12, -v12, v15, v14
	v_div_fmas_f32 v12, v12, v13, v15
	v_div_fixup_f32 v8, v12, v8, 1.0
	v_pk_fma_f32 v[56:57], v[10:11], v[8:9], v[56:57]
	v_lshl_add_u64 v[8:9], v[72:73], 0, s[28:29]
	v_mov_b32_e32 v8, v184
	v_mov_b32_e32 v9, v185
	v_mov_b32_e32 v10, v186
	v_mov_b32_e32 v11, v187
	s_waitcnt vmcnt(0)
	v_lshlrev_b32_e32 v14, 16, v9
	v_and_b32_e32 v15, 0xffff0000, v9
	v_lshlrev_b32_e32 v9, 16, v10
	v_lshlrev_b32_e32 v12, 16, v8
	v_and_b32_e32 v13, 0xffff0000, v8
	v_mul_f32_e32 v9, 0xbfb8aa3b, v9
	v_and_b32_e32 v16, 0xffff0000, v10
	v_mul_f32_e32 v8, 0xbfb8aa3b, v12
	v_exp_f32_e32 v10, v9
	v_mul_f32_e32 v9, 0xbfb8aa3b, v13
	v_exp_f32_e32 v8, v8
	v_exp_f32_e32 v9, v9
	v_lshlrev_b32_e32 v17, 16, v11
	v_and_b32_e32 v18, 0xffff0000, v11
	v_pk_add_f32 v[8:9], v[8:9], 1.0 op_sel_hi:[1,0]
	s_nop 0
	v_div_scale_f32 v11, s[24:25], v9, v9, 1.0
	v_rcp_f32_e32 v12, v11
	s_nop 0
	v_fma_f32 v13, -v11, v12, 1.0
	v_fmac_f32_e32 v12, v13, v12
	v_div_scale_f32 v13, vcc, 1.0, v9, 1.0
	v_mul_f32_e32 v19, v13, v12
	v_fma_f32 v20, -v11, v19, v13
	v_fmac_f32_e32 v19, v20, v12
	v_fma_f32 v11, -v11, v19, v13
	v_div_fmas_f32 v11, v11, v12, v19
	v_div_fixup_f32 v9, v11, v9, 1.0
	v_div_scale_f32 v11, s[24:25], v8, v8, 1.0
	v_rcp_f32_e32 v12, v11
	s_nop 0
	v_fma_f32 v13, -v11, v12, 1.0
	v_fmac_f32_e32 v12, v13, v12
	v_div_scale_f32 v13, vcc, 1.0, v8, 1.0
	v_mul_f32_e32 v19, v13, v12
	v_fma_f32 v20, -v11, v19, v13
	v_fmac_f32_e32 v19, v20, v12
	v_fma_f32 v11, -v11, v19, v13
	v_div_fmas_f32 v11, v11, v12, v19
	v_div_fixup_f32 v8, v11, v8, 1.0
	v_pk_fma_f32 v[48:49], v[4:5], v[8:9], v[48:49]
	v_mul_f32_e32 v4, 0xbfb8aa3b, v16
	v_exp_f32_e32 v11, v4
	s_nop 0
	v_pk_add_f32 v[4:5], v[10:11], 1.0 op_sel_hi:[1,0]
	s_nop 0
	v_div_scale_f32 v8, s[24:25], v5, v5, 1.0
	v_rcp_f32_e32 v9, v8
	s_nop 0
	v_fma_f32 v10, -v8, v9, 1.0
	v_fmac_f32_e32 v9, v10, v9
	v_div_scale_f32 v10, vcc, 1.0, v5, 1.0
	v_mul_f32_e32 v11, v10, v9
	v_fma_f32 v12, -v8, v11, v10
	v_fmac_f32_e32 v11, v12, v9
	v_fma_f32 v8, -v8, v11, v10
	v_div_fmas_f32 v8, v8, v9, v11
	v_div_fixup_f32 v5, v8, v5, 1.0
	v_div_scale_f32 v8, s[24:25], v4, v4, 1.0
	v_rcp_f32_e32 v9, v8
	s_nop 0
	v_fma_f32 v10, -v8, v9, 1.0
	v_fmac_f32_e32 v9, v10, v9
	v_div_scale_f32 v10, vcc, 1.0, v4, 1.0
	v_mul_f32_e32 v11, v10, v9
	v_fma_f32 v12, -v8, v11, v10
	v_fmac_f32_e32 v11, v12, v9
	v_fma_f32 v8, -v8, v11, v10
	v_div_fmas_f32 v8, v8, v9, v11
	v_div_fixup_f32 v4, v8, v4, 1.0
	v_pk_fma_f32 v[42:43], v[0:1], v[4:5], v[42:43]
	v_mul_f32_e32 v1, 0xbfb8aa3b, v17
	v_mul_f32_e32 v0, 0xbfb8aa3b, v14
	v_exp_f32_e32 v4, v1
	v_mul_f32_e32 v1, 0xbfb8aa3b, v15
	v_exp_f32_e32 v0, v0
	v_exp_f32_e32 v1, v1
	s_nop 0
	v_pk_add_f32 v[0:1], v[0:1], 1.0 op_sel_hi:[1,0]
	s_nop 0
	v_div_scale_f32 v5, s[24:25], v1, v1, 1.0
	v_rcp_f32_e32 v8, v5
	s_nop 0
	v_fma_f32 v9, -v5, v8, 1.0
	v_fmac_f32_e32 v8, v9, v8
	v_div_scale_f32 v9, vcc, 1.0, v1, 1.0
	v_mul_f32_e32 v10, v9, v8
	v_fma_f32 v11, -v5, v10, v9
	v_fmac_f32_e32 v10, v11, v8
	v_fma_f32 v5, -v5, v10, v9
	v_div_fmas_f32 v5, v5, v8, v10
	v_div_fixup_f32 v1, v5, v1, 1.0
	v_div_scale_f32 v5, s[24:25], v0, v0, 1.0
	v_rcp_f32_e32 v8, v5
	s_nop 0
	v_fma_f32 v9, -v5, v8, 1.0
	v_fmac_f32_e32 v8, v9, v8
	v_div_scale_f32 v9, vcc, 1.0, v0, 1.0
	v_mul_f32_e32 v10, v9, v8
	v_fma_f32 v11, -v5, v10, v9
	v_fmac_f32_e32 v10, v11, v8
	v_fma_f32 v5, -v5, v10, v9
	v_div_fmas_f32 v5, v5, v8, v10
	v_div_fixup_f32 v0, v5, v0, 1.0
	v_pk_fma_f32 v[50:51], v[6:7], v[0:1], v[50:51]
	v_mul_f32_e32 v0, 0xbfb8aa3b, v18
	v_exp_f32_e32 v5, v0
	s_nop 0
	v_pk_add_f32 v[0:1], v[4:5], 1.0 op_sel_hi:[1,0]
	s_nop 0
	v_div_scale_f32 v4, s[24:25], v1, v1, 1.0
	v_rcp_f32_e32 v5, v4
	s_nop 0
	v_fma_f32 v6, -v4, v5, 1.0
	v_fmac_f32_e32 v5, v6, v5
	v_div_scale_f32 v6, vcc, 1.0, v1, 1.0
	v_mul_f32_e32 v7, v6, v5
	v_fma_f32 v8, -v4, v7, v6
	v_fmac_f32_e32 v7, v8, v5
	v_fma_f32 v4, -v4, v7, v6
	v_div_fmas_f32 v4, v4, v5, v7
	v_div_fixup_f32 v1, v4, v1, 1.0
	v_div_scale_f32 v4, s[24:25], v0, v0, 1.0
	v_rcp_f32_e32 v5, v4
	s_nop 0
	v_fma_f32 v6, -v4, v5, 1.0
	v_fmac_f32_e32 v5, v6, v5
	v_div_scale_f32 v6, vcc, 1.0, v0, 1.0
	v_mul_f32_e32 v7, v6, v5
	v_fma_f32 v8, -v4, v7, v6
	v_fmac_f32_e32 v7, v8, v5
	v_fma_f32 v4, -v4, v7, v6
	v_div_fmas_f32 v4, v4, v5, v7
	v_div_fixup_f32 v0, v4, v0, 1.0
	v_pk_fma_f32 v[46:47], v[2:3], v[0:1], v[46:47]
	s_cbranch_scc1 .LBB0_81
.LBB0_84:
	s_lshl_b32 s24, s51, 11
	s_mov_b32 s25, 0
	v_lshl_add_u64 v[166:167], v[54:55], 0, s[24:25]
	global_load_dwordx4 v[168:171], v[166:167], off
	v_lshl_add_u64 v[166:167], v[62:63], 0, s[24:25]
	global_load_dwordx4 v[172:175], v[166:167], off
	v_lshl_add_u64 v[166:167], v[64:65], 0, s[24:25]
	global_load_dwordx4 v[176:179], v[166:167], off
	v_lshl_add_u64 v[166:167], v[66:67], 0, s[24:25]
	global_load_dwordx4 v[180:183], v[166:167], off
	v_lshl_add_u64 v[166:167], v[72:73], 0, s[24:25]
	global_load_dwordx4 v[184:187], v[166:167], off
	s_lshl_b32 s24, s51, 10
	v_mov_b32_e32 v4, v208
	s_add_u32 s24, s47, s24
	s_addc_u32 s25, s48, 0
	v_ashrrev_i32_e32 v2, 6, v4
	v_bfe_u32 v3, v4, 3, 3
	v_lshlrev_b32_e32 v5, 3, v2
	v_lshrrev_b32_e32 v6, 3, v4
	v_or_b32_e32 v8, v5, v3
	v_mov_b64_e32 v[0:1], s[24:25]
	v_bitop3_b32 v7, v6, v4, 7 bitop3:0x28
	v_mad_i64_i32 v[0:1], s[24:25], v8, s84, v[0:1]
	v_lshlrev_b32_e32 v94, 10, v2
	v_lshlrev_b32_e32 v128, 4, v7
	v_readfirstlane_b32 s24, v94
	v_lshl_add_u64 v[0:1], v[0:1], 0, v[128:129]
	s_mov_b32 m0, s24
	s_mov_b64 s[24:25], 0x18000
	v_add_u32_e32 v10, 0x1000, v94
	s_waitcnt lgkmcnt(0)
	s_barrier
	v_lshl_add_u64 v[8:9], v[0:1], 0, s[24:25]
	v_readfirstlane_b32 s24, v10
	global_load_lds_dwordx4 v[0:1], off
	s_mov_b32 m0, s24
	v_cmp_gt_i32_e64 s[36:37], 2, v2
	global_load_lds_dwordx4 v[8:9], off
	s_and_saveexec_b64 s[42:43], s[36:37]
	s_mov_b64 s[44:45], 0x1000
	s_cbranch_execz .LBB0_86
	s_mov_b64 s[24:25], 0x30000
	v_add_u32_e32 v8, 0x2000, v94
	v_lshl_add_u64 v[0:1], v[0:1], 0, s[24:25]
	v_readfirstlane_b32 s24, v8
	s_mov_b32 m0, s24
	s_nop 0
	global_load_lds_dwordx4 v[0:1], off

.LBB0_263:
	s_or_b64 exec, exec, s[40:41]
	s_ashr_i32 s40, s26, 6
	s_ashr_i32 s41, s40, 31
	s_lshl_b64 s[56:57], s[40:41], 7
	v_lshrrev_b32_e32 v5, 2, v1
	v_lshlrev_b32_e32 v4, 3, v3
	s_lshl_b64 s[56:57], s[56:57], s64
	v_lshlrev_b32_e32 v3, 5, v0
	v_and_b32_e32 v5, 8, v5
	v_and_b32_e32 v2, 3, v2
	s_lshl_b64 s[56:57], s[56:57], 1
	v_or3_b32 v2, v3, v5, v2
	s_add_u32 s56, s62, s56
	v_ashrrev_i32_e32 v3, 31, v2
	s_addc_u32 s57, s63, s57
	v_lshlrev_b64 v[2:3], s64, v[2:3]
	v_lshl_add_u64 v[2:3], v[2:3], 1, s[56:57]
	v_lshlrev_b32_e32 v128, 1, v4
	v_lshl_add_u64 v[48:49], v[2:3], 0, v[128:129]
	v_mad_u64_u32 v[2:3], s[56:57], v0, s84, v[42:43]
	v_add_u32_e32 v3, 0x4000, v2
	v_lshl_add_u64 v[50:51], v[48:49], 0, s[46:47]
	v_readfirstlane_b32 s26, v3
	v_add_u32_e32 v3, 0x4400, v2
	s_mov_b32 m0, s26
	v_readfirstlane_b32 s26, v3
	v_add_u32_e32 v3, 0x4800, v2
	global_load_lds_dwordx4 v[48:49], off
	s_mov_b32 m0, s26
	v_readfirstlane_b32 s26, v3
	v_add_u32_e32 v2, 0x4c00, v2
	global_load_lds_dwordx4 v[50:51], off
	v_lshl_add_u64 v[52:53], v[50:51], 0, s[52:53]
	s_mov_b32 m0, s26
	v_readfirstlane_b32 s26, v2
	global_load_lds_dwordx4 v[52:53], off
	v_lshl_add_u64 v[54:55], v[48:49], 0, s[48:49]
	s_mov_b32 m0, s26
	v_and_b32_e32 v2, 7, v1
	global_load_lds_dwordx4 v[54:55], off
	v_lshlrev_b32_e32 v3, 7, v1
	v_lshlrev_b32_e32 v2, 4, v2
	v_and_b32_e32 v3, 0x780, v3
	v_bitop3_b32 v1, v2, v1, 48 bitop3:0x78
	v_lshlrev_b32_e32 v57, 12, v0
	v_mov_b32_e32 v4, 0
	v_or_b32_e32 v43, v1, v3
	s_mov_b32 s28, 64
	v_bitop3_b32 v56, v1, 64, v3 bitop3:0x36
	v_add_u32_e32 v58, 0x4000, v57
	s_mov_b32 s41, 0
	s_mov_b32 s26, 0
	v_mov_b32_e32 v5, v4
	v_mov_b32_e32 v6, v4
	v_mov_b32_e32 v7, v4
	v_mov_b32_e32 v0, v4
	v_mov_b32_e32 v1, v4
	v_mov_b32_e32 v2, v4
	v_mov_b32_e32 v3, v4
	v_mov_b32_e32 v8, v4
	v_mov_b32_e32 v9, v4
	v_mov_b32_e32 v10, v4
	v_mov_b32_e32 v11, v4
	v_mov_b32_e32 v12, v4
	v_mov_b32_e32 v13, v4
	v_mov_b32_e32 v14, v4
	v_mov_b32_e32 v15, v4
	v_mov_b32_e32 v16, v4
	v_mov_b32_e32 v17, v4
	v_mov_b32_e32 v18, v4
	v_mov_b32_e32 v19, v4
	v_mov_b32_e32 v20, v4
	v_mov_b32_e32 v21, v4
	v_mov_b32_e32 v22, v4
	v_mov_b32_e32 v23, v4
	v_mov_b32_e32 v24, v4
	v_mov_b32_e32 v25, v4
	v_mov_b32_e32 v26, v4
	v_mov_b32_e32 v27, v4
	v_mov_b32_e32 v28, v4
	v_mov_b32_e32 v29, v4
	v_mov_b32_e32 v30, v4
	v_mov_b32_e32 v31, v4
	v_mov_b32_e32 v32, v4
	v_mov_b32_e32 v33, v4
	v_mov_b32_e32 v34, v4
	v_mov_b32_e32 v35, v4
	v_mov_b32_e32 v36, v4
	v_mov_b32_e32 v37, v4
	v_mov_b32_e32 v38, v4
	v_mov_b32_e32 v39, v4
	s_cmp_gt_u32 s65, 1
	s_cbranch_scc0 .Lr80_p1
	s_mov_b32 s71, 0x8000
	v_add_u32_e32 v59, s71, v42
	s_lshl_b64 s[56:57], s[28:29], 1
	v_readfirstlane_b32 s58, v59
	v_add_u32_e32 v62, 0x1000, v59
	v_lshl_add_u64 v[60:61], v[40:41], 0, s[56:57]
	s_mov_b32 m0, s58
	v_readfirstlane_b32 s58, v62
	global_load_lds_dwordx4 v[60:61], off
	v_lshl_add_u64 v[60:61], v[44:45], 0, s[56:57]
	s_mov_b32 m0, s58
	s_nop 0
	global_load_lds_dwordx4 v[60:61], off
	s_and_saveexec_b64 s[58:59], s[38:39]
	s_cbranch_execz .Lr80p_noA3
	v_add_u32_e32 v59, 0x2000, v59
	v_lshl_add_u64 v[60:61], s[28:29], 1, v[46:47]
	v_readfirstlane_b32 s72, v59
	s_mov_b32 m0, s72
	s_nop 0
	global_load_lds_dwordx4 v[60:61], off

.Lr80_p1:
	s_movk_i32 s28, 0x80
.LBB0_266:
	s_add_i32 s58, s26, 1
	s_cmp_lt_u32 s58, s65
	s_cbranch_scc1 .Lr80_cnt
	s_waitcnt vmcnt(0)
	s_branch .Lr80_wd
.Lr80_cnt:
	s_cmp_lg_u64 s[38:39], 0
	s_cbranch_scc1 .Lr80_w7
	s_waitcnt vmcnt(6)
	s_branch .Lr80_wd
.Lr80_w7:
	s_waitcnt vmcnt(7)
.Lr80_wd:
	s_waitcnt lgkmcnt(0)
	s_barrier
	v_add_u32_e32 v60, s41, v58
	v_or_b32_e32 v59, s41, v43
	v_or_b32_e32 v116, s41, v56
	v_add_u32_e32 v117, v60, v43
	v_add_u32_e32 v118, v60, v56
	ds_read_b128 v[60:63], v59
	ds_read_b128 v[64:67], v59 offset:2048
	ds_read_b128 v[68:71], v59 offset:4096
	ds_read_b128 v[72:75], v59 offset:6144
	ds_read_b128 v[76:79], v59 offset:8192
	ds_read_b128 v[80:83], v117
	ds_read_b128 v[84:87], v117 offset:2048
	ds_read_b128 v[88:91], v116
	ds_read_b128 v[92:95], v116 offset:2048
	ds_read_b128 v[96:99], v116 offset:4096
	ds_read_b128 v[100:103], v116 offset:6144
	ds_read_b128 v[104:107], v116 offset:8192
	ds_read_b128 v[108:111], v118
	ds_read_b128 v[112:115], v118 offset:2048
	s_waitcnt lgkmcnt(7)
	v_mfma_f32_16x16x32_bf16 v[36:39], v[80:83], v[60:63], v[36:39]
	v_mfma_f32_16x16x32_bf16 v[32:35], v[84:87], v[60:63], v[32:35]
	v_mfma_f32_16x16x32_bf16 v[28:31], v[80:83], v[64:67], v[28:31]
	v_mfma_f32_16x16x32_bf16 v[24:27], v[84:87], v[64:67], v[24:27]
	v_mfma_f32_16x16x32_bf16 v[20:23], v[80:83], v[68:71], v[20:23]
	v_mfma_f32_16x16x32_bf16 v[16:19], v[84:87], v[68:71], v[16:19]
	v_mfma_f32_16x16x32_bf16 v[12:15], v[80:83], v[72:75], v[12:15]
	v_mfma_f32_16x16x32_bf16 v[0:3], v[80:83], v[76:79], v[0:3]
	v_mfma_f32_16x16x32_bf16 v[4:7], v[84:87], v[76:79], v[4:7]
	v_mfma_f32_16x16x32_bf16 v[8:11], v[84:87], v[72:75], v[8:11]
	s_waitcnt lgkmcnt(0)
	s_barrier
	s_add_i32 s58, s26, 2
	s_cmp_lt_u32 s58, s65
	s_cbranch_scc0 .Lr80_nd
	s_mov_b32 s71, s41
	v_add_u32_e32 v59, s71, v42
	s_lshl_b64 s[56:57], s[28:29], 1
	v_readfirstlane_b32 s58, v59
	v_add_u32_e32 v62, 0x1000, v59
	v_lshl_add_u64 v[60:61], v[40:41], 0, s[56:57]
	s_mov_b32 m0, s58
	v_readfirstlane_b32 s58, v62
	global_load_lds_dwordx4 v[60:61], off
	v_lshl_add_u64 v[60:61], v[44:45], 0, s[56:57]
	s_mov_b32 m0, s58
	s_nop 0
	global_load_lds_dwordx4 v[60:61], off
	s_and_saveexec_b64 s[58:59], s[38:39]
	s_cbranch_execz .Lr80i_noA3
	v_add_u32_e32 v59, 0x2000, v59
	v_lshl_add_u64 v[60:61], s[28:29], 1, v[46:47]
	v_readfirstlane_b32 s72, v59
	s_mov_b32 m0, s72
	s_nop 0
	global_load_lds_dwordx4 v[60:61], off

.Lr80_nd:
	s_nop 0
	v_mfma_f32_16x16x32_bf16 v[36:39], v[108:111], v[88:91], v[36:39]
	v_mfma_f32_16x16x32_bf16 v[32:35], v[112:115], v[88:91], v[32:35]
	v_mfma_f32_16x16x32_bf16 v[28:31], v[108:111], v[92:95], v[28:31]
	v_mfma_f32_16x16x32_bf16 v[24:27], v[112:115], v[92:95], v[24:27]
	v_mfma_f32_16x16x32_bf16 v[20:23], v[108:111], v[96:99], v[20:23]
	v_mfma_f32_16x16x32_bf16 v[16:19], v[112:115], v[96:99], v[16:19]
	v_mfma_f32_16x16x32_bf16 v[12:15], v[108:111], v[100:103], v[12:15]
	v_mfma_f32_16x16x32_bf16 v[8:11], v[112:115], v[100:103], v[8:11]
	v_mfma_f32_16x16x32_bf16 v[0:3], v[108:111], v[104:107], v[0:3]
	v_mfma_f32_16x16x32_bf16 v[4:7], v[112:115], v[104:107], v[4:7]
	s_add_i32 s26, s26, 1
	s_add_i32 s28, s28, 64
	s_xor_b32 s41, s41, 0x8000
	s_cmp_lg_u32 s26, s65
	s_cbranch_scc1 .LBB0_266
